# P4 row statistics: lane^16 / lane^32 exchanges by v_permlane16/32_swap instead of 32 serial ds_bpermute round trips
# speedup vs baseline: 1.0027x; 1.0005x over previous
.LBB0_614:
	v_mov_b32_e32 v130, v125
	v_mov_b32_e32 v131, v126
	v_mov_b32_e32 v132, v124
	v_mov_b32_e32 v133, v127
	v_pk_add_f32 v[130:131], v[130:131], v[132:133]
	v_mov_b32_e32 v132, v121
	v_mov_b32_e32 v133, v122
	v_mov_b32_e32 v134, v120
	v_mov_b32_e32 v135, v123
	v_pk_add_f32 v[132:133], v[132:133], v[134:135]
	v_and_b32_e32 v129, 64, v231
	v_add_f32_e32 v130, v130, v131
	v_pk_add_f32 v[132:133], v[132:133], v[132:133] op_sel_hi:[0,1]
	v_xor_b32_e32 v128, 16, v231
	v_add_u32_e32 v129, 64, v129
	v_add_f32_e32 v131, 0, v130
	v_add_f32_e32 v135, v116, v117
	v_add_f32_e32 v137, v118, v119
	v_mov_b32_e32 v134, v108
	v_mov_b32_e32 v136, v109
	v_mov_b32_e32 v132, v110
	v_mov_b32_e32 v130, v111
	v_cmp_lt_i32_e32 vcc, v128, v129
	v_pk_add_f32 v[134:135], v[134:135], v[136:137]
	v_pk_add_f32 v[130:131], v[132:133], v[130:131]
	v_cndmask_b32_e32 v128, v231, v128, vcc
	v_pk_add_f32 v[130:131], v[134:135], v[130:131]
	v_lshlrev_b32_e32 v128, 2, v128
	v_add_f32_e32 v130, v130, v131
	v_mov_b32_e32 v131, v130
	s_nop 1
	v_permlane16_swap_b32_e32 v131, v130
	v_xor_b32_e32 v132, 32, v231
	v_cmp_lt_i32_e32 vcc, v132, v129
	v_mov_b32_e32 v134, v125
	v_mov_b32_e32 v133, v124
	v_cndmask_b32_e32 v129, v231, v132, vcc
	v_lshlrev_b32_e32 v129, 2, v129
	s_waitcnt lgkmcnt(0)
	v_add_f32_e32 v130, v130, v131
	v_mov_b32_e32 v131, v130
	s_nop 1
	v_permlane32_swap_b32_e32 v131, v130
	v_mov_b32_e32 v135, v121
	s_lshl_b32 s0, s26, 3
	v_cmp_gt_u32_e32 vcc, 16, v231
	s_add_i32 s2, s0, 0
	s_waitcnt lgkmcnt(0)
	v_add_f32_e32 v130, v130, v131
	v_fmamk_f32 v132, v130, 0xbc800000, v127
	v_fmac_f32_e32 v134, 0xbc800000, v130
	v_fmamk_f32 v131, v130, 0xbc800000, v126
	v_fmac_f32_e32 v133, 0xbc800000, v130
	v_mul_f32_e32 v134, v134, v134
	v_mul_f32_e32 v132, v132, v132
	v_fmac_f32_e32 v134, v133, v133
	v_fmac_f32_e32 v132, v131, v131
	v_add_f32_e32 v131, v134, v132
	v_fmamk_f32 v133, v130, 0xbc800000, v123
	v_mov_b32_e32 v134, v120
	v_fmac_f32_e32 v135, 0xbc800000, v130
	v_fmamk_f32 v132, v130, 0xbc800000, v122
	v_fmac_f32_e32 v134, 0xbc800000, v130
	v_mul_f32_e32 v135, v135, v135
	v_mul_f32_e32 v133, v133, v133
	v_fmac_f32_e32 v135, v134, v134
	v_fmac_f32_e32 v133, v132, v132
	v_add_f32_e32 v132, v135, v133
	v_mov_b32_e32 v135, v117
	v_fmamk_f32 v133, v130, 0xbc800000, v119
	v_mov_b32_e32 v134, v116
	v_fmac_f32_e32 v135, 0xbc800000, v130
	v_add_f32_e32 v131, v131, v132
	v_fmamk_f32 v132, v130, 0xbc800000, v118
	v_fmac_f32_e32 v134, 0xbc800000, v130
	v_mul_f32_e32 v135, v135, v135
	v_mul_f32_e32 v133, v133, v133
	v_fmac_f32_e32 v135, v134, v134
	v_fmac_f32_e32 v133, v132, v132
	v_add_f32_e32 v132, v135, v133
	v_mov_b32_e32 v135, v109
	v_fmamk_f32 v133, v130, 0xbc800000, v111
	v_mov_b32_e32 v134, v108
	v_fmac_f32_e32 v135, 0xbc800000, v130
	v_add_f32_e32 v131, v132, v131
	v_fmamk_f32 v132, v130, 0xbc800000, v110
	v_fmac_f32_e32 v134, 0xbc800000, v130
	v_mul_f32_e32 v135, v135, v135
	v_mul_f32_e32 v133, v133, v133
	v_fmac_f32_e32 v135, v134, v134
	v_fmac_f32_e32 v133, v132, v132
	v_add_f32_e32 v132, v135, v133
	v_add_f32_e32 v131, v132, v131
	v_mov_b32_e32 v132, v131
	s_nop 1
	v_permlane16_swap_b32_e32 v132, v131
	s_barrier
	s_waitcnt lgkmcnt(0)
	v_add_f32_e32 v131, v131, v132
	v_mov_b32_e32 v132, v131
	s_nop 1
	v_permlane32_swap_b32_e32 v132, v131
	s_and_saveexec_b64 s[0:1], vcc
	s_cbranch_execz .LBB0_616
	s_lshl_b32 s3, s9, 11
	s_add_i32 s3, s2, s3
	v_mul_f32_e32 v130, 0x3c800000, v130
	v_lshl_add_u32 v133, v231, 5, s3
	s_waitcnt lgkmcnt(0)
	v_add_f32_e32 v131, v131, v132
	ds_write_b64 v133, v[130:131]
.LBB0_616:
	s_or_b64 exec, exec, s[0:1]
	v_mov_b32_e32 v130, v113
	v_mov_b32_e32 v131, v114
	s_waitcnt lgkmcnt(0)
	v_mov_b32_e32 v132, v112
	v_mov_b32_e32 v133, v115
	v_pk_add_f32 v[130:131], v[130:131], v[132:133]
	v_mov_b32_e32 v132, v105
	v_mov_b32_e32 v133, v106
	v_mov_b32_e32 v134, v104
	v_mov_b32_e32 v135, v107
	v_pk_add_f32 v[132:133], v[132:133], v[134:135]
	v_add_f32_e32 v130, v130, v131
	v_pk_add_f32 v[132:133], v[132:133], v[132:133] op_sel_hi:[0,1]
	v_add_f32_e32 v131, 0, v130
	v_add_f32_e32 v135, v100, v101
	v_add_f32_e32 v137, v102, v103
	v_mov_b32_e32 v134, v92
	v_mov_b32_e32 v136, v93
	v_mov_b32_e32 v132, v94
	v_mov_b32_e32 v130, v95
	v_pk_add_f32 v[134:135], v[134:135], v[136:137]
	v_pk_add_f32 v[130:131], v[132:133], v[130:131]
	v_mov_b32_e32 v133, v112
	v_pk_add_f32 v[130:131], v[134:135], v[130:131]
	v_mov_b32_e32 v134, v113
	v_add_f32_e32 v130, v130, v131
	v_mov_b32_e32 v131, v130
	s_nop 1
	v_permlane16_swap_b32_e32 v131, v130
	v_mov_b32_e32 v135, v105
	s_waitcnt lgkmcnt(0)
	v_add_f32_e32 v130, v130, v131
	v_mov_b32_e32 v131, v130
	s_nop 1
	v_permlane32_swap_b32_e32 v131, v130
	s_waitcnt lgkmcnt(0)
	v_add_f32_e32 v130, v130, v131
	v_fmamk_f32 v132, v130, 0xbc800000, v115
	v_fmac_f32_e32 v134, 0xbc800000, v130
	v_fmamk_f32 v131, v130, 0xbc800000, v114
	v_fmac_f32_e32 v133, 0xbc800000, v130
	v_mul_f32_e32 v134, v134, v134
	v_mul_f32_e32 v132, v132, v132
	v_fmac_f32_e32 v134, v133, v133
	v_fmac_f32_e32 v132, v131, v131
	v_add_f32_e32 v131, v134, v132
	v_fmamk_f32 v133, v130, 0xbc800000, v107
	v_mov_b32_e32 v134, v104
	v_fmac_f32_e32 v135, 0xbc800000, v130
	v_fmamk_f32 v132, v130, 0xbc800000, v106
	v_fmac_f32_e32 v134, 0xbc800000, v130
	v_mul_f32_e32 v135, v135, v135
	v_mul_f32_e32 v133, v133, v133
	v_fmac_f32_e32 v135, v134, v134
	v_fmac_f32_e32 v133, v132, v132
	v_add_f32_e32 v132, v135, v133
	v_mov_b32_e32 v135, v101
	v_fmamk_f32 v133, v130, 0xbc800000, v103
	v_mov_b32_e32 v134, v100
	v_fmac_f32_e32 v135, 0xbc800000, v130
	v_add_f32_e32 v131, v131, v132
	v_fmamk_f32 v132, v130, 0xbc800000, v102
	v_fmac_f32_e32 v134, 0xbc800000, v130
	v_mul_f32_e32 v135, v135, v135
	v_mul_f32_e32 v133, v133, v133
	v_fmac_f32_e32 v135, v134, v134
	v_fmac_f32_e32 v133, v132, v132
	v_add_f32_e32 v132, v135, v133
	v_mov_b32_e32 v135, v93
	v_fmamk_f32 v133, v130, 0xbc800000, v95
	v_mov_b32_e32 v134, v92
	v_fmac_f32_e32 v135, 0xbc800000, v130
	v_add_f32_e32 v131, v132, v131
	v_fmamk_f32 v132, v130, 0xbc800000, v94
	v_fmac_f32_e32 v134, 0xbc800000, v130
	v_mul_f32_e32 v135, v135, v135
	v_mul_f32_e32 v133, v133, v133
	v_fmac_f32_e32 v135, v134, v134
	v_fmac_f32_e32 v133, v132, v132
	v_add_f32_e32 v132, v135, v133
	v_add_f32_e32 v131, v132, v131
	v_mov_b32_e32 v132, v131
	s_nop 1
	v_permlane16_swap_b32_e32 v132, v131
	s_waitcnt lgkmcnt(0)
	v_add_f32_e32 v131, v131, v132
	v_mov_b32_e32 v132, v131
	s_nop 1
	v_permlane32_swap_b32_e32 v132, v131
	s_and_saveexec_b64 s[0:1], vcc
	s_cbranch_execz .LBB0_618
	s_lshl_b32 s3, s9, 11
	s_add_i32 s3, s2, s3
	v_mul_f32_e32 v130, 0x3c800000, v130
	v_lshl_add_u32 v133, v231, 5, s3
	s_waitcnt lgkmcnt(0)
	v_add_f32_e32 v131, v131, v132
	ds_write_b64 v133, v[130:131] offset:512
.LBB0_618:
	s_or_b64 exec, exec, s[0:1]
	v_mov_b32_e32 v130, v97
	v_mov_b32_e32 v131, v98
	s_waitcnt lgkmcnt(0)
	v_mov_b32_e32 v132, v96
	v_mov_b32_e32 v133, v99
	v_pk_add_f32 v[130:131], v[130:131], v[132:133]
	v_mov_b32_e32 v132, v89
	v_mov_b32_e32 v133, v90
	v_mov_b32_e32 v134, v88
	v_mov_b32_e32 v135, v91
	v_pk_add_f32 v[132:133], v[132:133], v[134:135]
	v_add_f32_e32 v130, v130, v131
	v_pk_add_f32 v[132:133], v[132:133], v[132:133] op_sel_hi:[0,1]
	v_add_f32_e32 v131, 0, v130
	v_add_f32_e32 v135, v84, v85
	v_add_f32_e32 v137, v86, v87
	v_mov_b32_e32 v134, v76
	v_mov_b32_e32 v136, v77
	v_mov_b32_e32 v132, v78
	v_mov_b32_e32 v130, v79
	v_pk_add_f32 v[134:135], v[134:135], v[136:137]
	v_pk_add_f32 v[130:131], v[132:133], v[130:131]
	v_mov_b32_e32 v133, v96
	v_pk_add_f32 v[130:131], v[134:135], v[130:131]
	v_mov_b32_e32 v134, v97
	v_add_f32_e32 v130, v130, v131
	v_mov_b32_e32 v131, v130
	s_nop 1
	v_permlane16_swap_b32_e32 v131, v130
	v_mov_b32_e32 v135, v89
	s_waitcnt lgkmcnt(0)
	v_add_f32_e32 v130, v130, v131
	v_mov_b32_e32 v131, v130
	s_nop 1
	v_permlane32_swap_b32_e32 v131, v130
	s_waitcnt lgkmcnt(0)
	v_add_f32_e32 v130, v130, v131
	v_fmamk_f32 v132, v130, 0xbc800000, v99
	v_fmac_f32_e32 v134, 0xbc800000, v130
	v_fmamk_f32 v131, v130, 0xbc800000, v98
	v_fmac_f32_e32 v133, 0xbc800000, v130
	v_mul_f32_e32 v134, v134, v134
	v_mul_f32_e32 v132, v132, v132
	v_fmac_f32_e32 v134, v133, v133
	v_fmac_f32_e32 v132, v131, v131
	v_add_f32_e32 v131, v134, v132
	v_fmamk_f32 v133, v130, 0xbc800000, v91
	v_mov_b32_e32 v134, v88
	v_fmac_f32_e32 v135, 0xbc800000, v130
	v_fmamk_f32 v132, v130, 0xbc800000, v90
	v_fmac_f32_e32 v134, 0xbc800000, v130
	v_mul_f32_e32 v135, v135, v135
	v_mul_f32_e32 v133, v133, v133
	v_fmac_f32_e32 v135, v134, v134
	v_fmac_f32_e32 v133, v132, v132
	v_add_f32_e32 v132, v135, v133
	v_mov_b32_e32 v135, v85
	v_fmamk_f32 v133, v130, 0xbc800000, v87
	v_mov_b32_e32 v134, v84
	v_fmac_f32_e32 v135, 0xbc800000, v130
	v_add_f32_e32 v131, v131, v132
	v_fmamk_f32 v132, v130, 0xbc800000, v86
	v_fmac_f32_e32 v134, 0xbc800000, v130
	v_mul_f32_e32 v135, v135, v135
	v_mul_f32_e32 v133, v133, v133
	v_fmac_f32_e32 v135, v134, v134
	v_fmac_f32_e32 v133, v132, v132
	v_add_f32_e32 v132, v135, v133
	v_mov_b32_e32 v135, v77
	v_fmamk_f32 v133, v130, 0xbc800000, v79
	v_mov_b32_e32 v134, v76
	v_fmac_f32_e32 v135, 0xbc800000, v130
	v_add_f32_e32 v131, v132, v131
	v_fmamk_f32 v132, v130, 0xbc800000, v78
	v_fmac_f32_e32 v134, 0xbc800000, v130
	v_mul_f32_e32 v135, v135, v135
	v_mul_f32_e32 v133, v133, v133
	v_fmac_f32_e32 v135, v134, v134
	v_fmac_f32_e32 v133, v132, v132
	v_add_f32_e32 v132, v135, v133
	v_add_f32_e32 v131, v132, v131
	v_mov_b32_e32 v132, v131
	s_nop 1
	v_permlane16_swap_b32_e32 v132, v131
	s_waitcnt lgkmcnt(0)
	v_add_f32_e32 v131, v131, v132
	v_mov_b32_e32 v132, v131
	s_nop 1
	v_permlane32_swap_b32_e32 v132, v131
	s_and_saveexec_b64 s[0:1], vcc
	s_cbranch_execz .LBB0_620
	s_lshl_b32 s3, s9, 11
	s_add_i32 s3, s2, s3
	v_mul_f32_e32 v130, 0x3c800000, v130
	v_lshl_add_u32 v133, v231, 5, s3
	s_waitcnt lgkmcnt(0)
	v_add_f32_e32 v131, v131, v132
	ds_write_b64 v133, v[130:131] offset:1024
.LBB0_620:
	s_or_b64 exec, exec, s[0:1]
	v_mov_b32_e32 v130, v81
	v_mov_b32_e32 v131, v82
	s_waitcnt lgkmcnt(0)
	v_mov_b32_e32 v132, v80
	v_mov_b32_e32 v133, v83
	v_pk_add_f32 v[130:131], v[130:131], v[132:133]
	v_mov_b32_e32 v132, v73
	v_mov_b32_e32 v133, v74
	v_mov_b32_e32 v134, v72
	v_mov_b32_e32 v135, v75
	v_pk_add_f32 v[132:133], v[132:133], v[134:135]
	v_add_f32_e32 v130, v130, v131
	v_pk_add_f32 v[132:133], v[132:133], v[132:133] op_sel_hi:[0,1]
	v_add_f32_e32 v131, 0, v130
	v_add_f32_e32 v135, v68, v69
	v_add_f32_e32 v137, v70, v71
	v_mov_b32_e32 v134, v64
	v_mov_b32_e32 v136, v65
	v_mov_b32_e32 v132, v66
	v_mov_b32_e32 v130, v67
	v_pk_add_f32 v[134:135], v[134:135], v[136:137]
	v_pk_add_f32 v[130:131], v[132:133], v[130:131]
	v_mov_b32_e32 v133, v80
	v_pk_add_f32 v[130:131], v[134:135], v[130:131]
	v_mov_b32_e32 v134, v81
	v_add_f32_e32 v130, v130, v131
	v_mov_b32_e32 v131, v130
	s_nop 1
	v_permlane16_swap_b32_e32 v131, v130
	v_mov_b32_e32 v135, v73
	s_waitcnt lgkmcnt(0)
	v_add_f32_e32 v130, v130, v131
	v_mov_b32_e32 v131, v130
	s_nop 1
	v_permlane32_swap_b32_e32 v131, v130
	s_waitcnt lgkmcnt(0)
	v_add_f32_e32 v130, v130, v131
	v_fmamk_f32 v132, v130, 0xbc800000, v83
	v_fmac_f32_e32 v134, 0xbc800000, v130
	v_fmamk_f32 v131, v130, 0xbc800000, v82
	v_fmac_f32_e32 v133, 0xbc800000, v130
	v_mul_f32_e32 v134, v134, v134
	v_mul_f32_e32 v132, v132, v132
	v_fmac_f32_e32 v134, v133, v133
	v_fmac_f32_e32 v132, v131, v131
	v_add_f32_e32 v131, v134, v132
	v_fmamk_f32 v133, v130, 0xbc800000, v75
	v_mov_b32_e32 v134, v72
	v_fmac_f32_e32 v135, 0xbc800000, v130
	v_fmamk_f32 v132, v130, 0xbc800000, v74
	v_fmac_f32_e32 v134, 0xbc800000, v130
	v_mul_f32_e32 v135, v135, v135
	v_mul_f32_e32 v133, v133, v133
	v_fmac_f32_e32 v135, v134, v134
	v_fmac_f32_e32 v133, v132, v132
	v_add_f32_e32 v132, v135, v133
	v_mov_b32_e32 v135, v69
	v_fmamk_f32 v133, v130, 0xbc800000, v71
	v_mov_b32_e32 v134, v68
	v_fmac_f32_e32 v135, 0xbc800000, v130
	v_add_f32_e32 v131, v131, v132
	v_fmamk_f32 v132, v130, 0xbc800000, v70
	v_fmac_f32_e32 v134, 0xbc800000, v130
	v_mul_f32_e32 v135, v135, v135
	v_mul_f32_e32 v133, v133, v133
	v_fmac_f32_e32 v135, v134, v134
	v_fmac_f32_e32 v133, v132, v132
	v_add_f32_e32 v132, v135, v133
	v_mov_b32_e32 v135, v65
	v_fmamk_f32 v133, v130, 0xbc800000, v67
	v_mov_b32_e32 v134, v64
	v_fmac_f32_e32 v135, 0xbc800000, v130
	v_add_f32_e32 v131, v132, v131
	v_fmamk_f32 v132, v130, 0xbc800000, v66
	v_fmac_f32_e32 v134, 0xbc800000, v130
	v_mul_f32_e32 v135, v135, v135
	v_mul_f32_e32 v133, v133, v133
	v_fmac_f32_e32 v135, v134, v134
	v_fmac_f32_e32 v133, v132, v132
	v_add_f32_e32 v132, v135, v133
	v_add_f32_e32 v131, v132, v131
	v_mov_b32_e32 v132, v131
	s_nop 1
	v_permlane16_swap_b32_e32 v132, v131
	s_waitcnt lgkmcnt(0)
	v_add_f32_e32 v131, v131, v132
	v_mov_b32_e32 v132, v131
	s_nop 1
	v_permlane32_swap_b32_e32 v132, v131
	s_and_saveexec_b64 s[0:1], vcc
	s_cbranch_execz .LBB0_622
	s_lshl_b32 s3, s9, 11
	s_add_i32 s3, s2, s3
	v_mul_f32_e32 v130, 0x3c800000, v130
	v_lshl_add_u32 v133, v231, 5, s3
	s_waitcnt lgkmcnt(0)
	v_add_f32_e32 v131, v131, v132
	ds_write_b64 v133, v[130:131] offset:1536
.LBB0_622:
	s_or_b64 exec, exec, s[0:1]
	v_mov_b32_e32 v130, v61
	v_mov_b32_e32 v131, v62
	s_waitcnt lgkmcnt(0)
	v_mov_b32_e32 v132, v60
	v_mov_b32_e32 v133, v63
	v_pk_add_f32 v[130:131], v[130:131], v[132:133]
	v_mov_b32_e32 v132, v57
	v_mov_b32_e32 v133, v58
	v_mov_b32_e32 v134, v56
	v_mov_b32_e32 v135, v59
	v_pk_add_f32 v[132:133], v[132:133], v[134:135]
	v_add_f32_e32 v130, v130, v131
	v_pk_add_f32 v[132:133], v[132:133], v[132:133] op_sel_hi:[0,1]
	v_add_f32_e32 v131, 0, v130
	v_add_f32_e32 v135, v52, v53
	v_add_f32_e32 v137, v54, v55
	v_mov_b32_e32 v134, v44
	v_mov_b32_e32 v136, v45
	v_mov_b32_e32 v132, v46
	v_mov_b32_e32 v130, v47
	v_pk_add_f32 v[134:135], v[134:135], v[136:137]
	v_pk_add_f32 v[130:131], v[132:133], v[130:131]
	v_mov_b32_e32 v133, v60
	v_pk_add_f32 v[130:131], v[134:135], v[130:131]
	v_mov_b32_e32 v134, v61
	v_add_f32_e32 v130, v130, v131
	v_mov_b32_e32 v131, v130
	s_nop 1
	v_permlane16_swap_b32_e32 v131, v130
	v_mov_b32_e32 v135, v57
	s_waitcnt lgkmcnt(0)
	v_add_f32_e32 v130, v130, v131
	v_mov_b32_e32 v131, v130
	s_nop 1
	v_permlane32_swap_b32_e32 v131, v130
	s_waitcnt lgkmcnt(0)
	v_add_f32_e32 v130, v130, v131
	v_fmamk_f32 v132, v130, 0xbc800000, v63
	v_fmac_f32_e32 v134, 0xbc800000, v130
	v_fmamk_f32 v131, v130, 0xbc800000, v62
	v_fmac_f32_e32 v133, 0xbc800000, v130
	v_mul_f32_e32 v134, v134, v134
	v_mul_f32_e32 v132, v132, v132
	v_fmac_f32_e32 v134, v133, v133
	v_fmac_f32_e32 v132, v131, v131
	v_add_f32_e32 v131, v134, v132
	v_fmamk_f32 v133, v130, 0xbc800000, v59
	v_mov_b32_e32 v134, v56
	v_fmac_f32_e32 v135, 0xbc800000, v130
	v_fmamk_f32 v132, v130, 0xbc800000, v58
	v_fmac_f32_e32 v134, 0xbc800000, v130
	v_mul_f32_e32 v135, v135, v135
	v_mul_f32_e32 v133, v133, v133
	v_fmac_f32_e32 v135, v134, v134
	v_fmac_f32_e32 v133, v132, v132
	v_add_f32_e32 v132, v135, v133
	v_mov_b32_e32 v135, v53
	v_fmamk_f32 v133, v130, 0xbc800000, v55
	v_mov_b32_e32 v134, v52
	v_fmac_f32_e32 v135, 0xbc800000, v130
	v_add_f32_e32 v131, v131, v132
	v_fmamk_f32 v132, v130, 0xbc800000, v54
	v_fmac_f32_e32 v134, 0xbc800000, v130
	v_mul_f32_e32 v135, v135, v135
	v_mul_f32_e32 v133, v133, v133
	v_fmac_f32_e32 v135, v134, v134
	v_fmac_f32_e32 v133, v132, v132
	v_add_f32_e32 v132, v135, v133
	v_mov_b32_e32 v135, v45
	v_fmamk_f32 v133, v130, 0xbc800000, v47
	v_mov_b32_e32 v134, v44
	v_fmac_f32_e32 v135, 0xbc800000, v130
	v_add_f32_e32 v131, v132, v131
	v_fmamk_f32 v132, v130, 0xbc800000, v46
	v_fmac_f32_e32 v134, 0xbc800000, v130
	v_mul_f32_e32 v135, v135, v135
	v_mul_f32_e32 v133, v133, v133
	v_fmac_f32_e32 v135, v134, v134
	v_fmac_f32_e32 v133, v132, v132
	v_add_f32_e32 v132, v135, v133
	v_add_f32_e32 v131, v132, v131
	v_mov_b32_e32 v132, v131
	s_nop 1
	v_permlane16_swap_b32_e32 v132, v131
	s_waitcnt lgkmcnt(0)
	v_add_f32_e32 v131, v131, v132
	v_mov_b32_e32 v132, v131
	s_nop 1
	v_permlane32_swap_b32_e32 v132, v131
	s_and_saveexec_b64 s[0:1], vcc
	s_cbranch_execz .LBB0_624
	s_lshl_b32 s3, s9, 11
	s_add_i32 s3, s2, s3
	v_mul_f32_e32 v130, 0x3c800000, v130
	v_lshl_add_u32 v133, v231, 5, s3
	s_waitcnt lgkmcnt(0)
	v_add_f32_e32 v131, v131, v132
	ds_write_b64 v133, v[130:131] offset:4096
.LBB0_624:
	s_or_b64 exec, exec, s[0:1]
	v_mov_b32_e32 v130, v49
	v_mov_b32_e32 v131, v50
	s_waitcnt lgkmcnt(0)
	v_mov_b32_e32 v132, v48
	v_mov_b32_e32 v133, v51
	v_pk_add_f32 v[130:131], v[130:131], v[132:133]
	v_mov_b32_e32 v132, v41
	v_mov_b32_e32 v133, v42
	v_mov_b32_e32 v134, v40
	v_mov_b32_e32 v135, v43
	v_pk_add_f32 v[132:133], v[132:133], v[134:135]
	v_add_f32_e32 v130, v130, v131
	v_pk_add_f32 v[132:133], v[132:133], v[132:133] op_sel_hi:[0,1]
	v_add_f32_e32 v131, 0, v130
	v_add_f32_e32 v135, v36, v37
	v_add_f32_e32 v137, v38, v39
	v_mov_b32_e32 v134, v28
	v_mov_b32_e32 v136, v29
	v_mov_b32_e32 v132, v30
	v_mov_b32_e32 v130, v31
	v_pk_add_f32 v[134:135], v[134:135], v[136:137]
	v_pk_add_f32 v[130:131], v[132:133], v[130:131]
	v_mov_b32_e32 v133, v48
	v_pk_add_f32 v[130:131], v[134:135], v[130:131]
	v_mov_b32_e32 v134, v49
	v_add_f32_e32 v130, v130, v131
	v_mov_b32_e32 v131, v130
	s_nop 1
	v_permlane16_swap_b32_e32 v131, v130
	v_mov_b32_e32 v135, v41
	s_waitcnt lgkmcnt(0)
	v_add_f32_e32 v130, v130, v131
	v_mov_b32_e32 v131, v130
	s_nop 1
	v_permlane32_swap_b32_e32 v131, v130
	s_waitcnt lgkmcnt(0)
	v_add_f32_e32 v130, v130, v131
	v_fmamk_f32 v132, v130, 0xbc800000, v51
	v_fmac_f32_e32 v134, 0xbc800000, v130
	v_fmamk_f32 v131, v130, 0xbc800000, v50
	v_fmac_f32_e32 v133, 0xbc800000, v130
	v_mul_f32_e32 v134, v134, v134
	v_mul_f32_e32 v132, v132, v132
	v_fmac_f32_e32 v134, v133, v133
	v_fmac_f32_e32 v132, v131, v131
	v_add_f32_e32 v131, v134, v132
	v_fmamk_f32 v133, v130, 0xbc800000, v43
	v_mov_b32_e32 v134, v40
	v_fmac_f32_e32 v135, 0xbc800000, v130
	v_fmamk_f32 v132, v130, 0xbc800000, v42
	v_fmac_f32_e32 v134, 0xbc800000, v130
	v_mul_f32_e32 v135, v135, v135
	v_mul_f32_e32 v133, v133, v133
	v_fmac_f32_e32 v135, v134, v134
	v_fmac_f32_e32 v133, v132, v132
	v_add_f32_e32 v132, v135, v133
	v_mov_b32_e32 v135, v37
	v_fmamk_f32 v133, v130, 0xbc800000, v39
	v_mov_b32_e32 v134, v36
	v_fmac_f32_e32 v135, 0xbc800000, v130
	v_add_f32_e32 v131, v131, v132
	v_fmamk_f32 v132, v130, 0xbc800000, v38
	v_fmac_f32_e32 v134, 0xbc800000, v130
	v_mul_f32_e32 v135, v135, v135
	v_mul_f32_e32 v133, v133, v133
	v_fmac_f32_e32 v135, v134, v134
	v_fmac_f32_e32 v133, v132, v132
	v_add_f32_e32 v132, v135, v133
	v_mov_b32_e32 v135, v29
	v_fmamk_f32 v133, v130, 0xbc800000, v31
	v_mov_b32_e32 v134, v28
	v_fmac_f32_e32 v135, 0xbc800000, v130
	v_add_f32_e32 v131, v132, v131
	v_fmamk_f32 v132, v130, 0xbc800000, v30
	v_fmac_f32_e32 v134, 0xbc800000, v130
	v_mul_f32_e32 v135, v135, v135
	v_mul_f32_e32 v133, v133, v133
	v_fmac_f32_e32 v135, v134, v134
	v_fmac_f32_e32 v133, v132, v132
	v_add_f32_e32 v132, v135, v133
	v_add_f32_e32 v131, v132, v131
	v_mov_b32_e32 v132, v131
	s_nop 1
	v_permlane16_swap_b32_e32 v132, v131
	s_waitcnt lgkmcnt(0)
	v_add_f32_e32 v131, v131, v132
	v_mov_b32_e32 v132, v131
	s_nop 1
	v_permlane32_swap_b32_e32 v132, v131
	s_and_saveexec_b64 s[0:1], vcc
	s_cbranch_execz .LBB0_626
	s_lshl_b32 s3, s9, 11
	s_add_i32 s3, s2, s3
	v_mul_f32_e32 v130, 0x3c800000, v130
	v_lshl_add_u32 v133, v231, 5, s3
	s_waitcnt lgkmcnt(0)
	v_add_f32_e32 v131, v131, v132
	ds_write_b64 v133, v[130:131] offset:4608
.LBB0_626:
	s_or_b64 exec, exec, s[0:1]
	v_mov_b32_e32 v130, v33
	v_mov_b32_e32 v131, v34
	s_waitcnt lgkmcnt(0)
	v_mov_b32_e32 v132, v32
	v_mov_b32_e32 v133, v35
	v_pk_add_f32 v[130:131], v[130:131], v[132:133]
	v_mov_b32_e32 v132, v25
	v_mov_b32_e32 v133, v26
	v_mov_b32_e32 v134, v24
	v_mov_b32_e32 v135, v27
	v_pk_add_f32 v[132:133], v[132:133], v[134:135]
	v_add_f32_e32 v130, v130, v131
	v_pk_add_f32 v[132:133], v[132:133], v[132:133] op_sel_hi:[0,1]
	v_add_f32_e32 v131, 0, v130
	v_add_f32_e32 v135, v20, v21
	v_add_f32_e32 v137, v22, v23
	v_mov_b32_e32 v134, v12
	v_mov_b32_e32 v136, v13
	v_mov_b32_e32 v132, v14
	v_mov_b32_e32 v130, v15
	v_pk_add_f32 v[134:135], v[134:135], v[136:137]
	v_pk_add_f32 v[130:131], v[132:133], v[130:131]
	v_mov_b32_e32 v133, v32
	v_pk_add_f32 v[130:131], v[134:135], v[130:131]
	v_mov_b32_e32 v134, v33
	v_add_f32_e32 v130, v130, v131
	v_mov_b32_e32 v131, v130
	s_nop 1
	v_permlane16_swap_b32_e32 v131, v130
	v_mov_b32_e32 v135, v25
	s_waitcnt lgkmcnt(0)
	v_add_f32_e32 v130, v130, v131
	v_mov_b32_e32 v131, v130
	s_nop 1
	v_permlane32_swap_b32_e32 v131, v130
	s_waitcnt lgkmcnt(0)
	v_add_f32_e32 v130, v130, v131
	v_fmamk_f32 v132, v130, 0xbc800000, v35
	v_fmac_f32_e32 v134, 0xbc800000, v130
	v_fmamk_f32 v131, v130, 0xbc800000, v34
	v_fmac_f32_e32 v133, 0xbc800000, v130
	v_mul_f32_e32 v134, v134, v134
	v_mul_f32_e32 v132, v132, v132
	v_fmac_f32_e32 v134, v133, v133
	v_fmac_f32_e32 v132, v131, v131
	v_add_f32_e32 v131, v134, v132
	v_fmamk_f32 v133, v130, 0xbc800000, v27
	v_mov_b32_e32 v134, v24
	v_fmac_f32_e32 v135, 0xbc800000, v130
	v_fmamk_f32 v132, v130, 0xbc800000, v26
	v_fmac_f32_e32 v134, 0xbc800000, v130
	v_mul_f32_e32 v135, v135, v135
	v_mul_f32_e32 v133, v133, v133
	v_fmac_f32_e32 v135, v134, v134
	v_fmac_f32_e32 v133, v132, v132
	v_add_f32_e32 v132, v135, v133
	v_mov_b32_e32 v135, v21
	v_fmamk_f32 v133, v130, 0xbc800000, v23
	v_mov_b32_e32 v134, v20
	v_fmac_f32_e32 v135, 0xbc800000, v130
	v_add_f32_e32 v131, v131, v132
	v_fmamk_f32 v132, v130, 0xbc800000, v22
	v_fmac_f32_e32 v134, 0xbc800000, v130
	v_mul_f32_e32 v135, v135, v135
	v_mul_f32_e32 v133, v133, v133
	v_fmac_f32_e32 v135, v134, v134
	v_fmac_f32_e32 v133, v132, v132
	v_add_f32_e32 v132, v135, v133
	v_mov_b32_e32 v135, v13
	v_fmamk_f32 v133, v130, 0xbc800000, v15
	v_mov_b32_e32 v134, v12
	v_fmac_f32_e32 v135, 0xbc800000, v130
	v_add_f32_e32 v131, v132, v131
	v_fmamk_f32 v132, v130, 0xbc800000, v14
	v_fmac_f32_e32 v134, 0xbc800000, v130
	v_mul_f32_e32 v135, v135, v135
	v_mul_f32_e32 v133, v133, v133
	v_fmac_f32_e32 v135, v134, v134
	v_fmac_f32_e32 v133, v132, v132
	v_add_f32_e32 v132, v135, v133
	v_add_f32_e32 v131, v132, v131
	v_mov_b32_e32 v132, v131
	s_nop 1
	v_permlane16_swap_b32_e32 v132, v131
	s_waitcnt lgkmcnt(0)
	v_add_f32_e32 v131, v131, v132
	v_mov_b32_e32 v132, v131
	s_nop 1
	v_permlane32_swap_b32_e32 v132, v131
	s_and_saveexec_b64 s[0:1], vcc
	s_cbranch_execz .LBB0_628
	s_lshl_b32 s3, s9, 11
	s_add_i32 s3, s2, s3
	v_mul_f32_e32 v130, 0x3c800000, v130
	v_lshl_add_u32 v133, v231, 5, s3
	s_waitcnt lgkmcnt(0)
	v_add_f32_e32 v131, v131, v132
	ds_write_b64 v133, v[130:131] offset:5120
.LBB0_628:
	s_or_b64 exec, exec, s[0:1]
	v_mov_b32_e32 v130, v17
	v_mov_b32_e32 v131, v18
	s_waitcnt lgkmcnt(0)
	v_mov_b32_e32 v132, v16
	v_mov_b32_e32 v133, v19
	v_pk_add_f32 v[130:131], v[130:131], v[132:133]
	v_mov_b32_e32 v132, v9
	v_mov_b32_e32 v133, v10
	v_mov_b32_e32 v134, v8
	v_mov_b32_e32 v135, v11
	v_pk_add_f32 v[132:133], v[132:133], v[134:135]
	v_add_f32_e32 v130, v130, v131
	v_pk_add_f32 v[132:133], v[132:133], v[132:133] op_sel_hi:[0,1]
	v_add_f32_e32 v131, 0, v130
	v_add_f32_e32 v135, v4, v5
	v_add_f32_e32 v137, v6, v7
	v_mov_b32_e32 v134, v0
	v_mov_b32_e32 v136, v1
	v_mov_b32_e32 v132, v2
	v_mov_b32_e32 v130, v3
	v_pk_add_f32 v[134:135], v[134:135], v[136:137]
	v_pk_add_f32 v[130:131], v[132:133], v[130:131]
	v_mov_b32_e32 v133, v16
	v_pk_add_f32 v[130:131], v[134:135], v[130:131]
	v_mov_b32_e32 v134, v17
	v_add_f32_e32 v130, v130, v131
	v_mov_b32_e32 v131, v130
	s_nop 1
	v_permlane16_swap_b32_e32 v131, v130
	v_mov_b32_e32 v135, v9
	s_waitcnt lgkmcnt(0)
	v_add_f32_e32 v130, v130, v131
	v_mov_b32_e32 v131, v130
	s_nop 1
	v_permlane32_swap_b32_e32 v131, v130
	s_waitcnt lgkmcnt(0)
	v_add_f32_e32 v130, v130, v131
	v_fmamk_f32 v132, v130, 0xbc800000, v19
	v_fmac_f32_e32 v134, 0xbc800000, v130
	v_fmamk_f32 v131, v130, 0xbc800000, v18
	v_fmac_f32_e32 v133, 0xbc800000, v130
	v_mul_f32_e32 v134, v134, v134
	v_mul_f32_e32 v132, v132, v132
	v_fmac_f32_e32 v134, v133, v133
	v_fmac_f32_e32 v132, v131, v131
	v_add_f32_e32 v131, v134, v132
	v_fmamk_f32 v133, v130, 0xbc800000, v11
	v_mov_b32_e32 v134, v8
	v_fmac_f32_e32 v135, 0xbc800000, v130
	v_fmamk_f32 v132, v130, 0xbc800000, v10
	v_fmac_f32_e32 v134, 0xbc800000, v130
	v_mul_f32_e32 v135, v135, v135
	v_mul_f32_e32 v133, v133, v133
	v_fmac_f32_e32 v135, v134, v134
	v_fmac_f32_e32 v133, v132, v132
	v_add_f32_e32 v132, v135, v133
	v_mov_b32_e32 v135, v5
	v_fmamk_f32 v133, v130, 0xbc800000, v7
	v_mov_b32_e32 v134, v4
	v_fmac_f32_e32 v135, 0xbc800000, v130
	v_add_f32_e32 v131, v131, v132
	v_fmamk_f32 v132, v130, 0xbc800000, v6
	v_fmac_f32_e32 v134, 0xbc800000, v130
	v_mul_f32_e32 v135, v135, v135
	v_mul_f32_e32 v133, v133, v133
	v_fmac_f32_e32 v135, v134, v134
	v_fmac_f32_e32 v133, v132, v132
	v_add_f32_e32 v132, v135, v133
	v_mov_b32_e32 v135, v1
	v_fmamk_f32 v133, v130, 0xbc800000, v3
	v_mov_b32_e32 v134, v0
	v_fmac_f32_e32 v135, 0xbc800000, v130
	v_add_f32_e32 v131, v132, v131
	v_fmamk_f32 v132, v130, 0xbc800000, v2
	v_fmac_f32_e32 v134, 0xbc800000, v130
	v_mul_f32_e32 v135, v135, v135
	v_mul_f32_e32 v133, v133, v133
	v_fmac_f32_e32 v135, v134, v134
	v_fmac_f32_e32 v133, v132, v132
	v_add_f32_e32 v132, v135, v133
	v_add_f32_e32 v131, v132, v131
	v_mov_b32_e32 v128, v131
	s_nop 1
	v_permlane16_swap_b32_e32 v128, v131
	s_waitcnt lgkmcnt(0)
	v_add_f32_e32 v128, v131, v128
	v_mov_b32_e32 v129, v128
	s_nop 1
	v_permlane32_swap_b32_e32 v129, v128
	s_and_saveexec_b64 s[0:1], vcc
	s_cbranch_execz .LBB0_630
	s_lshl_b32 s3, s9, 11
	s_add_i32 s2, s2, s3
	v_mul_f32_e32 v130, 0x3c800000, v130
	v_lshl_add_u32 v132, v231, 5, s2
	s_waitcnt lgkmcnt(0)
	v_add_f32_e32 v131, v128, v129
	ds_write_b64 v132, v[130:131] offset:5632
